# ML_LOC: the four serialized conv-weight load pairs issued together at the item-loop top (before gate scan and barrier), one wait
# baseline (speedup 1.0000x reference)
; __device__ __forceinline__ float ex2(float x) { return __builtin_amdgcn_exp2f(x); }
; __device__ __forceinline__ void conv8_compute(const u32x4 (&xr)[4], const float* cw, int ch, float (&out)[8]) {
;     ...
;     for (int i = 0; i < 4; ++i) { const u32x4 x = xr[i]; const f32x4 w0 = *(const f32x4*)(cw + i * 1024 + ch), w1 = *(const f32x4*)(cw + i * 1024 + ch + 4);
; __device__ __forceinline__ void ml_local_phase(const bf16_t* P, const float* GATES, const float* cw, const float* b_i, const float* b_f, float* KV, float* MLOC, float* BLAST, LAS unsigned char* lds) {
;     ...
;     for (int item = blockIdx.x; item < 2048; item += gridDim.x) {
;         const int bh = item >> 7, h = bh & 7;
;         if (wid == 0) { float li, lf; gates_from(raw.ip, raw.fp, b_i, b_f, h, li, lf);
;             float bc = lf;
; #pragma unroll
;             for (int o = 1; o < 64; o <<= 1) { const float t = __shfl_up(bc, o); if (lane >= o) bc += t; }
;             const float u = li - bc, ml = wave_max(u); wkL[lane] = ex2(u - ml);
;             if (lane == 63) BLAST[item] = bc; if (lane == 0) MLOC[item] = ml; }
.LBB0_329:
	v_cndmask_b32_e64 v1, 0, 1, s[6:7]
	v_cmp_ne_u32_e64 s[54:55], 1, v1
	s_andn2_b64 vcc, exec, s[6:7]
	s_bfe_u32 s0, s18, 0x30007
	v_lshlrev_b32_e32 v100, 2, v55
	v_lshl_or_b32 v100, s0, 8, v100
	v_mov_b32_e32 v101, v0
	v_lshl_add_u64 v[100:101], s[8:9], 0, v[100:101]
	global_load_dwordx4 v[104:107], v[100:101], off offset:2048
	global_load_dwordx4 v[108:111], v[100:101], off offset:2064
	s_mov_b64 s[16:17], 0x1000
	v_lshl_add_u64 v[102:103], v[100:101], 0, s[16:17]
	global_load_dwordx4 v[112:115], v[102:103], off offset:2048
	global_load_dwordx4 v[116:119], v[102:103], off offset:2064
	s_mov_b64 s[16:17], 0x2000
	v_lshl_add_u64 v[102:103], v[100:101], 0, s[16:17]
	global_load_dwordx4 v[120:123], v[102:103], off offset:2048
	global_load_dwordx4 v[124:127], v[102:103], off offset:2064
	s_mov_b64 s[16:17], 0x3000
	v_lshl_add_u64 v[102:103], v[100:101], 0, s[16:17]
	global_load_dwordx4 v[128:131], v[102:103], off offset:2048
	global_load_dwordx4 v[132:135], v[102:103], off offset:2064
	s_cbranch_vccnz .LBB0_337
	v_readlane_b32 s16, v254, 29
	v_readlane_b32 s17, v254, 30
	s_load_dwordx2 s[16:17], s[16:17], 0x70
	s_lshl_b32 s5, s0, 2
	v_mov_b32_e32 v1, s5
	s_waitcnt lgkmcnt(0)
	global_load_dword v2, v1, s[10:11]
	v_add_u32_e32 v4, -1, v232
	global_load_dword v1, v1, s[16:17]
	v_cmp_lt_i32_e32 vcc, v4, v233
	s_mov_b32 s5, 0x3fb8aa3b
	s_mov_b64 s[56:57], -1
	v_cndmask_b32_e32 v4, v4, v232, vcc
	v_lshlrev_b32_e32 v4, 2, v4
	s_waitcnt vmcnt(1)
	v_add_f32_e32 v2, v45, v2
	s_waitcnt vmcnt(0)
	v_add_f32_e32 v1, v54, v1
	v_mul_f32_e32 v1, 0xbfb8aa3b, v1
	v_max_f32_e32 v3, 0, v1
	v_exp_f32_e64 v1, -|v1|
	s_nop 0
	v_add_f32_e32 v1, 1.0, v1
	v_log_f32_e32 v1, v1
	s_nop 0
	v_add_f32_e32 v1, v3, v1
	v_xor_b32_e32 v3, 0x80000000, v1
	ds_bpermute_b32 v3, v4, v3
	s_waitcnt lgkmcnt(0)
	v_sub_f32_e32 v3, v3, v1
	v_cndmask_b32_e64 v1, v3, -v1, s[42:43]
	v_add_u32_e32 v3, -2, v232
	v_cmp_lt_i32_e32 vcc, v3, v233
	s_nop 1
	v_cndmask_b32_e32 v3, v3, v232, vcc
	v_lshlrev_b32_e32 v3, 2, v3
	ds_bpermute_b32 v3, v3, v1
	s_waitcnt lgkmcnt(0)
	v_add_f32_e32 v3, v1, v3
	v_cndmask_b32_e64 v1, v3, v1, s[44:45]
	v_add_u32_e32 v3, -4, v232
	v_cmp_lt_i32_e32 vcc, v3, v233
	s_nop 1
	v_cndmask_b32_e32 v3, v3, v232, vcc
	v_lshlrev_b32_e32 v3, 2, v3
	ds_bpermute_b32 v3, v3, v1
	s_waitcnt lgkmcnt(0)
	v_add_f32_e32 v3, v1, v3
	v_cndmask_b32_e64 v1, v3, v1, s[46:47]
	v_add_u32_e32 v3, -8, v232
	v_cmp_lt_i32_e32 vcc, v3, v233
	s_nop 1
	v_cndmask_b32_e32 v3, v3, v232, vcc
	v_lshlrev_b32_e32 v3, 2, v3
	ds_bpermute_b32 v3, v3, v1
	s_waitcnt lgkmcnt(0)
	v_add_f32_e32 v3, v1, v3
	v_cndmask_b32_e64 v1, v3, v1, s[48:49]
	v_add_u32_e32 v3, -16, v232
	v_cmp_lt_i32_e32 vcc, v3, v233
	s_nop 1
	v_cndmask_b32_e32 v3, v3, v232, vcc
	v_lshlrev_b32_e32 v3, 2, v3
	ds_bpermute_b32 v3, v3, v1
	s_waitcnt lgkmcnt(0)
	v_add_f32_e32 v3, v1, v3
	v_cndmask_b32_e64 v3, v3, v1, s[50:51]
	v_subrev_u32_e32 v1, 32, v232
	v_cmp_lt_i32_e32 vcc, v1, v233
	s_nop 1
	v_cndmask_b32_e32 v1, v1, v232, vcc
	v_lshlrev_b32_e32 v1, 2, v1
	ds_bpermute_b32 v1, v1, v3
	v_cmp_lt_i32_e32 vcc, v235, v234
	s_waitcnt lgkmcnt(0)
	v_add_f32_e32 v1, v3, v1
	v_cndmask_b32_e64 v3, v1, v3, s[52:53]
	v_fma_f32 v2, v2, s5, -v3
	v_cndmask_b32_e32 v3, v232, v235, vcc
	v_lshlrev_b32_e32 v3, 2, v3
	ds_bpermute_b32 v3, v3, v2
	v_cmp_lt_i32_e32 vcc, v249, v234
	s_waitcnt lgkmcnt(0)
	v_max_f32_e32 v3, v3, v3
	v_cndmask_b32_e32 v4, v232, v249, vcc
	v_max_f32_e32 v3, v2, v3
	v_lshlrev_b32_e32 v4, 2, v4
	ds_bpermute_b32 v4, v4, v3
	v_cmp_lt_i32_e32 vcc, v250, v234
	s_waitcnt lgkmcnt(0)
	v_max_f32_e32 v4, v4, v4
	v_max_f32_e32 v3, v3, v4
	v_cndmask_b32_e32 v4, v232, v250, vcc
	v_lshlrev_b32_e32 v4, 2, v4
	ds_bpermute_b32 v4, v4, v3
	v_cmp_lt_i32_e32 vcc, v251, v234
	s_waitcnt lgkmcnt(0)
	v_max_f32_e32 v4, v4, v4
	v_max_f32_e32 v3, v3, v4
	v_cndmask_b32_e32 v4, v232, v251, vcc
	v_lshlrev_b32_e32 v4, 2, v4
	ds_bpermute_b32 v4, v4, v3
	v_cmp_lt_i32_e32 vcc, v196, v234
	s_waitcnt lgkmcnt(0)
	v_max_f32_e32 v4, v4, v4
	v_max_f32_e32 v3, v3, v4
	v_cndmask_b32_e32 v4, v232, v196, vcc
	v_lshlrev_b32_e32 v4, 2, v4
	ds_bpermute_b32 v4, v4, v3
	v_cmp_lt_i32_e32 vcc, v240, v234
	s_waitcnt lgkmcnt(0)
	v_max_f32_e32 v4, v4, v4
	v_max_f32_e32 v3, v3, v4
	v_cndmask_b32_e32 v4, v232, v240, vcc
	v_lshlrev_b32_e32 v4, 2, v4
	ds_bpermute_b32 v4, v4, v3
	v_cmp_gt_i32_e32 vcc, 63, v44
	s_waitcnt lgkmcnt(0)
	v_max_f32_e32 v4, v4, v4
	v_max_f32_e32 v4, v3, v4
	v_sub_f32_e32 v2, v2, v4
	v_exp_f32_e32 v2, v2
	ds_write_b32 v56, v2
	v_mov_b64_e32 v[2:3], 0x175e2000
	s_and_saveexec_b64 s[20:21], vcc
	s_cbranch_execz .LBB0_334
	v_cmp_eq_u32_e32 vcc, 0, v44
	s_mov_b64 s[56:57], 0
	v_mov_b64_e32 v[2:3], 0x175e2000
	s_and_saveexec_b64 s[58:59], vcc
	s_mov_b64 s[56:57], exec
	v_mov_b64_e32 v[2:3], 0x175e0000
	s_or_b64 exec, exec, s[58:59]
	s_orn2_b64 s[56:57], s[56:57], exec
	v_mov_b32_e32 v1, v4

; #define LAS __attribute__((address_space(3)))
; __device__ __forceinline__ unsigned pk2(float lo, float hi) { f32x2_t v = {lo, hi}; bf16x2_t b = __builtin_convertvector(v, bf16x2_t); return __builtin_bit_cast(unsigned, b); }
; __device__ __forceinline__ float ex2(float x) { return __builtin_amdgcn_exp2f(x); }
; __device__ __forceinline__ void conv8_compute(const u32x4 (&xr)[4], const float* cw, int ch, float (&out)[8]) {
;     ...
;     for (int i = 0; i < 4; ++i) { const u32x4 x = xr[i]; const f32x4 w0 = *(const f32x4*)(cw + i * 1024 + ch), w1 = *(const f32x4*)(cw + i * 1024 + ch + 4);
;         out[0] += w0[0] * __uint_as_float(x.x << 16); out[1] += w0[1] * __uint_as_float(x.x & 0xffff0000u); out[2] += w0[2] * __uint_as_float(x.y << 16); out[3] += w0[3] * __uint_as_float(x.y & 0xffff0000u);
;         out[4] += w1[0] * __uint_as_float(x.z << 16); out[5] += w1[1] * __uint_as_float(x.z & 0xffff0000u); out[6] += w1[2] * __uint_as_float(x.w << 16); out[7] += w1[3] * __uint_as_float(x.w & 0xffff0000u); }
; #pragma unroll
;     for (int e = 0; e < 8; ++e) out[e] = out[e] * __builtin_amdgcn_rcpf(1.0f + ex2(-out[e] * LOG2E));
; }
; __device__ __forceinline__ void ml_local_phase(const bf16_t* P, const float* GATES, const float* cw, const float* b_i, const float* b_f, float* KV, float* MLOC, float* BLAST, LAS unsigned char* lds) {
;     ...
;         __syncthreads();
;         { const int t = tid >> 3, c0 = (tid & 7) * 8; float kv[8]; conv8_compute(raw.kx, cw, 512 + h * 64 + c0, kv); const float wk = wkL[t];
; #pragma unroll
;           for (int e = 0; e < 8; ++e) *(LAS bf16_t*)(KT + (c0 + e) * 144 + t * 2) = (bf16_t)(pk2(kv[e] * wk, 0.f) & 0xffffu);
;           const int d0 = (tid & 7) * 16; const unsigned vv[8] = {raw.va.x, raw.va.y, raw.va.z, raw.va.w, raw.vc.x, raw.vc.y, raw.vc.z, raw.vc.w};
; #pragma unroll
;           for (int e = 0; e < 8; ++e) { *(LAS bf16_t*)(VT + (d0 + 2 * e) * 144 + t * 2) = (bf16_t)(vv[e] & 0xffffu); *(LAS bf16_t*)(VT + (d0 + 2 * e + 1) * 144 + t * 2) = (bf16_t)(vv[e] >> 16); } }
;         if (item + (int)gridDim.x < 2048) loc_load(raw, P, GATES, item + gridDim.x, tid, lane, wid);
.LBB0_337:
	s_waitcnt lgkmcnt(0)
	s_barrier
	v_lshlrev_b32_e32 v1, 16, v18
	s_movk_i32 s0, 0x1000
	s_mov_b64 s[16:17], 0x1800
	v_lshlrev_b32_e32 v11, 16, v22
	s_mov_b64 s[16:17], 0x2800
	s_add_i32 s5, s18, s14
	s_cmpk_gt_i32 s5, 0x7ff
	s_cselect_b64 s[20:21], -1, 0
	s_waitcnt vmcnt(0)
	v_fma_f32 v10, v104, v1, 0
	v_and_b32_e32 v1, 0xffff0000, v18
	v_fma_f32 v9, v105, v1, 0
	v_lshlrev_b32_e32 v1, 16, v19
	v_fma_f32 v8, v106, v1, 0
	v_and_b32_e32 v1, 0xffff0000, v19
	v_fma_f32 v7, v107, v1, 0
	v_lshlrev_b32_e32 v1, 16, v20
	v_fma_f32 v6, v108, v1, 0
	v_and_b32_e32 v1, 0xffff0000, v20
	v_fma_f32 v5, v109, v1, 0
	v_lshlrev_b32_e32 v1, 16, v21
	v_fma_f32 v4, v110, v1, 0
	v_and_b32_e32 v1, 0xffff0000, v21
	v_fma_f32 v1, v111, v1, 0
	s_movk_i32 s0, 0x2000
	s_mov_b64 s[16:17], 0x3800
	v_fmac_f32_e32 v10, v112, v11
	v_and_b32_e32 v11, 0xffff0000, v22
	v_fmac_f32_e32 v9, v113, v11
	v_lshlrev_b32_e32 v11, 16, v23
	v_fmac_f32_e32 v8, v114, v11
	v_and_b32_e32 v11, 0xffff0000, v23
	v_fmac_f32_e32 v7, v115, v11
	v_lshlrev_b32_e32 v11, 16, v24
	v_fmac_f32_e32 v6, v116, v11
	v_and_b32_e32 v11, 0xffff0000, v24
	v_fmac_f32_e32 v5, v117, v11
	v_lshlrev_b32_e32 v11, 16, v25
	v_fmac_f32_e32 v4, v118, v11
	v_and_b32_e32 v11, 0xffff0000, v25
	v_fmac_f32_e32 v1, v119, v11
	v_lshlrev_b32_e32 v11, 16, v26
	s_movk_i32 s0, 0x3000
	v_fmac_f32_e32 v10, v120, v11
	v_and_b32_e32 v11, 0xffff0000, v26
	v_fmac_f32_e32 v9, v121, v11
	v_lshlrev_b32_e32 v11, 16, v27
	v_fmac_f32_e32 v8, v122, v11
	v_and_b32_e32 v11, 0xffff0000, v27
	v_fmac_f32_e32 v7, v123, v11
	v_lshlrev_b32_e32 v11, 16, v28
	v_fmac_f32_e32 v6, v124, v11
	v_and_b32_e32 v11, 0xffff0000, v28
	v_fmac_f32_e32 v5, v125, v11
	v_lshlrev_b32_e32 v11, 16, v29
	v_fmac_f32_e32 v4, v126, v11
	v_and_b32_e32 v11, 0xffff0000, v29
	v_fmac_f32_e32 v1, v127, v11
	v_lshlrev_b32_e32 v2, 16, v30
	s_and_b64 vcc, exec, s[20:21]
	v_fmac_f32_e32 v10, v128, v2
	v_and_b32_e32 v2, 0xffff0000, v30
	v_fmac_f32_e32 v9, v129, v2
	v_mul_f32_e32 v3, 0xbfb8aa3b, v9
	v_exp_f32_e32 v3, v3
	v_lshlrev_b32_e32 v2, 16, v31
	v_fmac_f32_e32 v8, v130, v2
	v_and_b32_e32 v2, 0xffff0000, v31
	v_add_f32_e32 v3, 1.0, v3
	v_rcp_f32_e32 v3, v3
	v_fmac_f32_e32 v7, v131, v2
	v_lshlrev_b32_e32 v2, 16, v32
	v_fmac_f32_e32 v6, v132, v2
	v_mul_f32_e32 v3, v9, v3
	v_mul_f32_e32 v9, 0xbfb8aa3b, v8
	v_exp_f32_e32 v9, v9
	v_and_b32_e32 v2, 0xffff0000, v32
	v_fmac_f32_e32 v5, v133, v2
	v_lshlrev_b32_e32 v2, 16, v33
	v_add_f32_e32 v9, 1.0, v9
	v_rcp_f32_e32 v9, v9
	v_fmac_f32_e32 v4, v134, v2
	v_and_b32_e32 v2, 0xffff0000, v33
	v_fmac_f32_e32 v1, v135, v2
	v_mul_f32_e32 v8, v8, v9
	v_mul_f32_e32 v9, 0xbfb8aa3b, v7
	v_exp_f32_e32 v9, v9
	v_mul_f32_e32 v2, 0xbfb8aa3b, v10
	v_exp_f32_e32 v2, v2
	v_add_f32_e32 v9, 1.0, v9
	v_rcp_f32_e32 v9, v9
	v_add_f32_e32 v2, 1.0, v2
	v_rcp_f32_e32 v2, v2
	v_mul_f32_e32 v7, v7, v9
	v_mul_f32_e32 v9, 0xbfb8aa3b, v6
	v_exp_f32_e32 v9, v9
	v_mul_f32_e32 v2, v10, v2
	v_add_f32_e32 v9, 1.0, v9
	v_rcp_f32_e32 v9, v9
	s_nop 0
	v_mul_f32_e32 v6, v6, v9
	v_mul_f32_e32 v9, 0xbfb8aa3b, v5
	v_exp_f32_e32 v9, v9
	s_nop 0
	v_add_f32_e32 v9, 1.0, v9
	v_rcp_f32_e32 v9, v9
	s_nop 0
	v_mul_f32_e32 v5, v5, v9
	v_mul_f32_e32 v9, 0xbfb8aa3b, v4
	v_exp_f32_e32 v9, v9
	s_nop 0
	v_add_f32_e32 v9, 1.0, v9
	v_rcp_f32_e32 v9, v9
	s_nop 0
	v_mul_f32_e32 v4, v4, v9
	v_mul_f32_e32 v9, 0xbfb8aa3b, v1
	v_exp_f32_e32 v9, v9
	s_nop 0
	v_add_f32_e32 v9, 1.0, v9
	v_rcp_f32_e32 v9, v9
	s_nop 0
	v_mul_f32_e32 v1, v1, v9
	ds_read_b32 v9, v57
	s_waitcnt lgkmcnt(0)
	v_mul_f32_e32 v2, v9, v2
	v_cvt_pk_bf16_f32 v2, v2, s0
	ds_write_b16 v59, v2 offset:256
	v_mul_f32_e32 v2, v9, v3
	v_cvt_pk_bf16_f32 v2, v2, s0
	ds_write_b16 v59, v2 offset:400
	v_mul_f32_e32 v2, v9, v8
	v_cvt_pk_bf16_f32 v2, v2, s0
	ds_write_b16 v59, v2 offset:544
	v_mul_f32_e32 v2, v9, v7
	v_cvt_pk_bf16_f32 v2, v2, s0
	ds_write_b16 v59, v2 offset:688
	v_mul_f32_e32 v2, v9, v6
	v_cvt_pk_bf16_f32 v2, v2, s0
	ds_write_b16 v59, v2 offset:832
	v_mul_f32_e32 v2, v9, v5
	v_cvt_pk_bf16_f32 v2, v2, s0
	ds_write_b16 v59, v2 offset:976
	v_mul_f32_e32 v2, v9, v4
	v_mul_f32_e32 v1, v9, v1
	v_cvt_pk_bf16_f32 v2, v2, s0
	v_cvt_pk_bf16_f32 v1, v1, s0
	ds_write_b16 v59, v2 offset:1120
	ds_write_b16 v59, v1 offset:1264
	ds_write_b16 v60, v34 offset:9472
	ds_write_b16_d16_hi v60, v34 offset:9616
	ds_write_b16 v60, v35 offset:9760
	ds_write_b16_d16_hi v60, v35 offset:9904
	ds_write_b16 v60, v36 offset:10048
	ds_write_b16_d16_hi v60, v36 offset:10192
	ds_write_b16 v60, v37 offset:10336
	ds_write_b16_d16_hi v60, v37 offset:10480
	ds_write_b16 v60, v38 offset:10624
	ds_write_b16_d16_hi v60, v38 offset:10768
	ds_write_b16 v60, v39 offset:10912
	ds_write_b16_d16_hi v60, v39 offset:11056
	ds_write_b16 v60, v40 offset:11200
	ds_write_b16_d16_hi v60, v40 offset:11344
	ds_write_b16 v60, v41 offset:11488
	ds_write_b16_d16_hi v60, v41 offset:11632
	s_cbranch_vccnz .LBB0_351
	s_ashr_i32 s24, s5, 10
	s_ashr_i32 s25, s24, 31
	s_lshl_b32 s0, s5, 6
	s_lshl_b64 s[56:57], s[24:25], 13
	s_and_b32 s17, s0, 0x1fc0
	s_bfe_u32 s16, s5, 0x30007
	s_and_b64 vcc, exec, s[54:55]
	s_or_b32 s56, s56, s17
	s_cbranch_vccnz .LBB0_340
	v_mov_b32_e32 v3, s57
	v_or_b32_e32 v2, s56, v44
	v_readlane_b32 s24, v254, 46
	v_lshlrev_b64 v[2:3], 6, v[2:3]
	v_readlane_b32 s25, v254, 47
	s_lshl_b32 s0, s16, 2
	s_nop 0
	v_lshl_add_u64 v[2:3], s[24:25], 0, v[2:3]
	v_lshl_add_u64 v[2:3], v[2:3], 0, s[0:1]
	global_load_dword v45, v[2:3], off
	global_load_dword v54, v[2:3], off offset:32
